# attention second-half QK segment: finishSM row-sum/cvt/permlane VALU interleaved with QK MFMAs
# baseline (speedup 1.0000x reference)
.LBB0_2067:
	v_cndmask_b32_e64 v220, v162, v166, s[6:7]
	v_mul_f32_e32 v221, 0xbe0293ee, v220
	v_fmamk_f32 v82, v82, 0x3e0293ee, v221
	v_fmamk_f32 v83, v83, 0x3e0293ee, v221
	v_fmamk_f32 v84, v84, 0x3e0293ee, v221
	v_fmamk_f32 v85, v85, 0x3e0293ee, v221
	v_fmamk_f32 v86, v86, 0x3e0293ee, v221
	v_fmamk_f32 v87, v87, 0x3e0293ee, v221
	v_fmamk_f32 v88, v88, 0x3e0293ee, v221
	v_fmamk_f32 v89, v89, 0x3e0293ee, v221
	v_fmamk_f32 v90, v90, 0x3e0293ee, v221
	v_fmamk_f32 v91, v91, 0x3e0293ee, v221
	v_fmamk_f32 v92, v92, 0x3e0293ee, v221
	v_fmamk_f32 v93, v93, 0x3e0293ee, v221
	v_fmamk_f32 v94, v94, 0x3e0293ee, v221
	v_fmamk_f32 v95, v95, 0x3e0293ee, v221
	v_fmamk_f32 v96, v96, 0x3e0293ee, v221
	v_fmamk_f32 v97, v97, 0x3e0293ee, v221
	v_exp_f32_e32 v162, v82
	v_exp_f32_e32 v177, v83
	v_exp_f32_e32 v163, v84
	v_exp_f32_e32 v176, v85
	v_exp_f32_e32 v164, v86
	v_exp_f32_e32 v175, v87
	v_exp_f32_e32 v165, v88
	v_exp_f32_e32 v174, v89
	v_exp_f32_e32 v166, v90
	v_exp_f32_e32 v173, v91
	v_exp_f32_e32 v167, v92
	v_exp_f32_e32 v172, v93
	v_exp_f32_e32 v168, v94
	v_exp_f32_e32 v171, v95
	v_exp_f32_e32 v169, v96
	v_exp_f32_e32 v170, v97
	v_fmamk_f32 v230, v66, 0x3e0293ee, v221
	v_fmamk_f32 v231, v67, 0x3e0293ee, v221
	v_fmamk_f32 v232, v68, 0x3e0293ee, v221
	v_fmamk_f32 v233, v69, 0x3e0293ee, v221
	v_fmamk_f32 v234, v70, 0x3e0293ee, v221
	v_fmamk_f32 v223, v71, 0x3e0293ee, v221
	v_fmamk_f32 v224, v72, 0x3e0293ee, v221
	v_fmamk_f32 v225, v73, 0x3e0293ee, v221
	v_fmamk_f32 v226, v74, 0x3e0293ee, v221
	v_fmamk_f32 v227, v75, 0x3e0293ee, v221
	v_fmamk_f32 v228, v76, 0x3e0293ee, v221
	v_fmamk_f32 v229, v77, 0x3e0293ee, v221
	v_fmamk_f32 v222, v78, 0x3e0293ee, v221
	v_fmamk_f32 v235, v79, 0x3e0293ee, v221
	v_fmamk_f32 v236, v80, 0x3e0293ee, v221
	v_fmac_f32_e32 v221, 0x3e0293ee, v81
	ds_read_b128 v[66:69], v205 offset:32768
	ds_read_b128 v[70:73], v205 offset:40960
	ds_read_b128 v[238:241], v206 offset:32768
	ds_read_b128 v[242:245], v206 offset:40960
	v_exp_f32_e32 v230, v230
	v_exp_f32_e32 v231, v231
	s_waitcnt lgkmcnt(3)
	v_mfma_f32_32x32x16_bf16 v[82:97], v[66:69], v[126:129], 0
	v_exp_f32_e32 v232, v232
	v_exp_f32_e32 v233, v233
	v_exp_f32_e32 v234, v234
	v_exp_f32_e32 v223, v223
	v_exp_f32_e32 v224, v224
	v_exp_f32_e32 v225, v225
	v_exp_f32_e32 v226, v226
	s_waitcnt lgkmcnt(2)
	v_mfma_f32_32x32x16_bf16 v[66:81], v[70:73], v[126:129], 0
	v_exp_f32_e32 v227, v227
	v_exp_f32_e32 v228, v228
	v_exp_f32_e32 v229, v229
	v_exp_f32_e32 v237, v222
	v_exp_f32_e32 v235, v235
	v_exp_f32_e32 v236, v236
	s_waitcnt lgkmcnt(1)
	v_mfma_f32_32x32x16_bf16 v[82:97], v[238:241], v[122:125], v[82:97]
	s_waitcnt lgkmcnt(0)
	v_mfma_f32_32x32x16_bf16 v[66:81], v[242:245], v[122:125], v[66:81]
	v_exp_f32_e32 v248, v221
	ds_read_b128 v[238:241], v207 offset:32768
	ds_read_b128 v[242:245], v207 offset:40960
	s_waitcnt lgkmcnt(1)
	v_mfma_f32_32x32x16_bf16 v[82:97], v[238:241], v[118:121], v[82:97]
	v_add_f32_e32 v249, 0, v162
	v_add_f32_e32 v249, v177, v249
	v_add_f32_e32 v249, v163, v249
	v_add_f32_e32 v249, v176, v249
	v_add_f32_e32 v249, v164, v249
	s_waitcnt lgkmcnt(0)
	v_mfma_f32_32x32x16_bf16 v[66:81], v[242:245], v[118:121], v[66:81]
	v_add_f32_e32 v249, v175, v249
	v_add_f32_e32 v249, v165, v249
	v_add_f32_e32 v249, v174, v249
	v_add_f32_e32 v249, v166, v249
	v_add_f32_e32 v249, v173, v249
	ds_read_b128 v[238:241], v208 offset:32768
	ds_read_b128 v[242:245], v208 offset:40960
	s_waitcnt lgkmcnt(1)
	v_mfma_f32_32x32x16_bf16 v[82:97], v[238:241], v[114:117], v[82:97]
	v_add_f32_e32 v249, v167, v249
	v_add_f32_e32 v249, v172, v249
	v_add_f32_e32 v249, v168, v249
	v_add_f32_e32 v249, v171, v249
	v_add_f32_e32 v249, v169, v249
	s_waitcnt lgkmcnt(0)
	v_mfma_f32_32x32x16_bf16 v[66:81], v[242:245], v[114:117], v[66:81]
	v_add_f32_e32 v249, v170, v249
	v_add_f32_e32 v249, v230, v249
	v_add_f32_e32 v249, v231, v249
	v_add_f32_e32 v249, v232, v249
	v_add_f32_e32 v249, v233, v249
	ds_read_b128 v[238:241], v209 offset:32768
	ds_read_b128 v[242:245], v209 offset:40960
	s_waitcnt lgkmcnt(1)
	v_mfma_f32_32x32x16_bf16 v[82:97], v[238:241], v[110:113], v[82:97]
	v_add_f32_e32 v249, v234, v249
	v_add_f32_e32 v249, v223, v249
	v_add_f32_e32 v249, v224, v249
	v_add_f32_e32 v249, v225, v249
	v_add_f32_e32 v249, v226, v249
	s_waitcnt lgkmcnt(0)
	v_mfma_f32_32x32x16_bf16 v[66:81], v[242:245], v[110:113], v[66:81]
	v_add_f32_e32 v249, v227, v249
	v_add_f32_e32 v249, v228, v249
	v_add_f32_e32 v249, v229, v249
	v_add_f32_e32 v249, v237, v249
	v_add_f32_e32 v249, v235, v249
	ds_read_b128 v[238:241], v210 offset:32768
	ds_read_b128 v[242:245], v210 offset:40960
	s_waitcnt lgkmcnt(1)
	v_mfma_f32_32x32x16_bf16 v[82:97], v[238:241], v[106:109], v[82:97]
	v_add_f32_e32 v249, v236, v249
	v_add_f32_e32 v221, v248, v249
	v_mov_b32_e32 v222, v221
	v_cvt_pk_bf16_f32 v162, v162, v177
	v_cvt_pk_bf16_f32 v163, v163, v176
	s_waitcnt lgkmcnt(0)
	v_mfma_f32_32x32x16_bf16 v[66:81], v[242:245], v[106:109], v[66:81]
	v_cvt_pk_bf16_f32 v164, v164, v175
	v_cvt_pk_bf16_f32 v165, v165, v174
	v_cvt_pk_bf16_f32 v166, v166, v173
	v_cvt_pk_bf16_f32 v167, v167, v172
	v_cvt_pk_bf16_f32 v168, v168, v171
	ds_read_b128 v[238:241], v211 offset:32768
	ds_read_b128 v[242:245], v211 offset:40960
	s_waitcnt lgkmcnt(1)
	v_mfma_f32_32x32x16_bf16 v[82:97], v[238:241], v[102:105], v[82:97]
	v_cvt_pk_bf16_f32 v169, v169, v170
	v_cvt_pk_bf16_f32 v170, v230, v231
	v_cvt_pk_bf16_f32 v171, v232, v233
	v_cvt_pk_bf16_f32 v172, v234, v223
	v_cvt_pk_bf16_f32 v173, v224, v225
	s_waitcnt lgkmcnt(0)
	v_mfma_f32_32x32x16_bf16 v[66:81], v[242:245], v[102:105], v[66:81]
	v_cvt_pk_bf16_f32 v174, v226, v227
	v_cvt_pk_bf16_f32 v175, v228, v229
	v_cvt_pk_bf16_f32 v176, v237, v235
	v_cvt_pk_bf16_f32 v177, v236, v248
	s_nop 1
	v_permlane32_swap_b32_e32 v221, v222
	ds_read_b128 v[238:241], v212 offset:32768
	ds_read_b128 v[242:245], v212 offset:40960
	s_waitcnt lgkmcnt(1)
	v_mfma_f32_32x32x16_bf16 v[82:97], v[238:241], v[98:101], v[82:97]
	v_permlane32_swap_b32_e32 v162, v164
	v_permlane32_swap_b32_e32 v163, v165
	v_permlane32_swap_b32_e32 v166, v168
	v_permlane32_swap_b32_e32 v167, v169
	v_permlane32_swap_b32_e32 v170, v172
	s_waitcnt lgkmcnt(0)
	v_mfma_f32_32x32x16_bf16 v[66:81], v[242:245], v[98:101], v[66:81]
	v_permlane32_swap_b32_e32 v171, v173
	v_permlane32_swap_b32_e32 v174, v176
	v_permlane32_swap_b32_e32 v175, v177
	s_cmp_gt_u32 s51, 64
	s_cselect_b64 s[12:13], -1, 0
	s_and_b64 vcc, exec, s[12:13]
	s_cbranch_vccnz .LBB0_2069
	v_lshl_add_u64 v[138:139], s[10:11], 0, v[184:185]
	v_add_co_u32_e32 v130, vcc, 0x27800000, v138
	v_lshl_add_u64 v[140:141], s[10:11], 0, v[182:183]
	s_nop 0
	v_addc_co_u32_e32 v131, vcc, 0, v139, vcc
	v_add_co_u32_e32 v134, vcc, 0x27800000, v140
	s_nop 1
	v_addc_co_u32_e32 v135, vcc, 0, v141, vcc
	v_add_co_u32_e32 v138, vcc, 0x26700000, v138
	global_load_dwordx4 v[130:133], v[130:131], off
	s_nop 0
	global_load_dwordx4 v[134:137], v[134:135], off
	v_addc_co_u32_e32 v139, vcc, 0, v139, vcc
	v_add_co_u32_e32 v142, vcc, 0x26700000, v140
	s_nop 1
	v_addc_co_u32_e32 v143, vcc, 0, v141, vcc
	global_load_dwordx4 v[138:141], v[138:139], off
	s_nop 0
	global_load_dwordx4 v[142:145], v[142:143], off
